# neighbourhood attention QK^T: double-buffered Q/K fragment reads with counted waits (was read-wait-MFMA per k-step)
# speedup vs baseline: 1.0024x; 1.0024x over previous
; __device__ __forceinline__ int crow(int r, int hi) { return (r & 3) + 8 * (r >> 2) + 4 * hi; }
; template <int DK, bool QL>
; __device__ __forceinline__ void qkt(f32x16& p0, f32x16& p1, const bf16* Ks, const bf16x8* qr, const char* ql, int r32, int hi) {
;   p0 = f32x16{}; p1 = f32x16{};
; #pragma unroll
;   for (int d0 = 0; d0 < DK / 16; ++d0) { int cb = (d0 * 16 + hi * 8) * 2;
;     const bf16x8 qv = QL ? *reinterpret_cast<const bf16x8*>(ql + d0 * 1024) : qr[d0];
;     bf16x8 b0 = *reinterpret_cast<const bf16x8*>((const char*)Ks + kswz<DK>(r32, cb));
;     bf16x8 b1 = *reinterpret_cast<const bf16x8*>((const char*)Ks + kswz<DK>(32 + r32, cb));
;     p0 = __builtin_amdgcn_mfma_f32_32x32x16_bf16(b0, qv, p0, 0, 0, 0);
;     p1 = __builtin_amdgcn_mfma_f32_32x32x16_bf16(b1, qv, p1, 0, 0, 0); }
; }
; __device__ __forceinline__ void na_hook(f32x16& p0, f32x16& p1, int kr, int q_row, int q_col, int win_r, int win_c, const float* rpb, float inv_scale, int hi) {
;   const bool rowok = (kr >= win_r) && (kr < win_r + 8);
;   int ir = kr - q_row + 7; ir = ir < 0 ? 0 : (ir > 14 ? 14 : ir);
;   const float* rp = rpb + ir * 31;
; #pragma unroll
;   for (int r = 0; r < 16; ++r) {
;     const int kc = crow(r, hi);
;     { const bool ok = rowok && kc >= win_c && kc < win_c + 16; int ic = kc - q_col + 15; ic = ic < 0 ? 0 : (ic > 30 ? 30 : ic);
;       p0[r] = ok ? fmaf(rp[ic], inv_scale, p0[r]) : -1e30f; }
;     { const int kc2 = kc + 32; const bool ok = rowok && kc2 >= win_c && kc2 < win_c + 16; int ic = kc2 - q_col + 15; ic = ic < 0 ? 0 : (ic > 30 ? 30 : ic);
;       p1[r] = ok ? fmaf(rp[ic], inv_scale, p1[r]) : -1e30f; }
;   }
; }
.LBB0_449:
	ds_read_b128 v[2:5], v147
	ds_read_b128 v[6:9], v158 offset:49152
	ds_read_b128 v[10:13], v158 offset:57344
	ds_read_b128 v[164:167], v147 offset:1024
	ds_read_b128 v[168:171], v159 offset:49152
	ds_read_b128 v[172:175], v159 offset:57344
	v_readlane_b32 s36, v254, 26
	s_add_i32 s50, s36, s33
	s_add_i32 s48, s50, -2
	s_waitcnt lgkmcnt(4)
	v_mfma_f32_32x32x16_bf16 v[112:127], v[6:9], v[2:5], 0
	v_readlane_b32 s36, v255, 32
	s_cmp_lt_u32 s48, s36
	v_readlane_b32 s49, v255, 33
	s_cselect_b64 s[36:37], -1, 0
	s_cmp_ge_u32 s48, s49
	s_cselect_b64 s[48:49], -1, 0
	s_or_b64 s[36:37], s[36:37], s[48:49]
	s_waitcnt lgkmcnt(3)
	v_mfma_f32_32x32x16_bf16 v[96:111], v[10:13], v[2:5], 0
	ds_read_b128 v[2:5], v147 offset:2048
	ds_read_b128 v[6:9], v160 offset:49152
	ds_read_b128 v[10:13], v160 offset:57344
	v_readlane_b32 s48, v255, 48
	s_add_i32 s51, s48, s33
	s_add_i32 s48, s51, -2
	v_med3_i32 v0, s48, -7, 7
	s_movk_i32 s48, 0x7c
	v_mul_lo_u32 v0, v0, s48
	s_waitcnt lgkmcnt(4)
	v_mfma_f32_32x32x16_bf16 v[112:127], v[168:171], v[164:167], v[112:127]
	v_readlane_b32 s48, v255, 50
	v_add_u32_e32 v0, 0, v0
	v_readlane_b32 s49, v255, 51
	s_nor_b64 s[48:49], s[48:49], s[36:37]
	v_mov_b32_e32 v14, 0xf149f2ca
	s_waitcnt lgkmcnt(3)
	v_mfma_f32_32x32x16_bf16 v[96:111], v[172:175], v[164:167], v[96:111]
	ds_read_b128 v[164:167], v147 offset:3072
	ds_read_b128 v[168:171], v161 offset:49152
	ds_read_b128 v[172:175], v161 offset:57344
	s_waitcnt lgkmcnt(4)
	v_mfma_f32_32x32x16_bf16 v[112:127], v[6:9], v[2:5], v[112:127]
	s_waitcnt lgkmcnt(3)
	v_mfma_f32_32x32x16_bf16 v[96:111], v[10:13], v[2:5], v[96:111]
	ds_read_b128 v[2:5], v147 offset:4096
	ds_read_b128 v[6:9], v176 offset:49152
	ds_read_b128 v[10:13], v176 offset:57344
	s_waitcnt lgkmcnt(4)
	v_mfma_f32_32x32x16_bf16 v[112:127], v[168:171], v[164:167], v[112:127]
	s_waitcnt lgkmcnt(3)
	v_mfma_f32_32x32x16_bf16 v[96:111], v[172:175], v[164:167], v[96:111]
	ds_read_b128 v[164:167], v147 offset:5120
	ds_read_b128 v[168:171], v177 offset:49152
	ds_read_b128 v[172:175], v177 offset:57344
	s_waitcnt lgkmcnt(4)
	v_mfma_f32_32x32x16_bf16 v[112:127], v[6:9], v[2:5], v[112:127]
	s_waitcnt lgkmcnt(3)
	v_mfma_f32_32x32x16_bf16 v[96:111], v[10:13], v[2:5], v[96:111]
	ds_read_b128 v[2:5], v147 offset:6144
	ds_read_b128 v[6:9], v207 offset:49152
	ds_read_b128 v[10:13], v207 offset:57344
	s_waitcnt lgkmcnt(4)
	v_mfma_f32_32x32x16_bf16 v[112:127], v[168:171], v[164:167], v[112:127]
	s_waitcnt lgkmcnt(3)
	v_mfma_f32_32x32x16_bf16 v[96:111], v[172:175], v[164:167], v[96:111]
	ds_read_b128 v[164:167], v147 offset:7168
	ds_read_b128 v[168:171], v208 offset:49152
	ds_read_b128 v[172:175], v208 offset:57344
	s_waitcnt lgkmcnt(4)
	v_mfma_f32_32x32x16_bf16 v[112:127], v[6:9], v[2:5], v[112:127]
	s_waitcnt lgkmcnt(3)
	v_mfma_f32_32x32x16_bf16 v[96:111], v[10:13], v[2:5], v[96:111]
	s_waitcnt lgkmcnt(1)
	v_mfma_f32_32x32x16_bf16 v[112:127], v[168:171], v[164:167], v[112:127]
	s_waitcnt lgkmcnt(0)
	v_mfma_f32_32x32x16_bf16 v[96:111], v[172:175], v[164:167], v[96:111]
	v_add_u32_e32 v2, 0x10800, v0
	v_mov_b32_e32 v0, 0xf149f2ca
	v_lshl_add_u32 v162, v242, 2, v2
	ds_read_b32 v162, v162 offset:928
	v_lshl_add_u32 v178, v209, 2, v2
	ds_read_b32 v178, v178 offset:928
	v_lshl_add_u32 v179, v210, 2, v2
	ds_read_b32 v179, v179 offset:928
	v_lshl_add_u32 v180, v211, 2, v2
	ds_read_b32 v180, v180 offset:928
	v_lshl_add_u32 v201, v212, 2, v2
	ds_read_b32 v201, v201 offset:928
	v_lshl_add_u32 v202, v213, 2, v2
	ds_read_b32 v202, v202 offset:928
	v_lshl_add_u32 v168, v214, 2, v2
	ds_read_b32 v168, v168 offset:928
	v_lshl_add_u32 v169, v215, 2, v2
	ds_read_b32 v169, v169 offset:928
	v_lshl_add_u32 v170, v216, 2, v2
	ds_read_b32 v170, v170 offset:928
	v_lshl_add_u32 v171, v217, 2, v2
	ds_read_b32 v171, v171 offset:928
	v_lshl_add_u32 v190, v218, 2, v2
	ds_read_b32 v190, v190 offset:928
	v_lshl_add_u32 v191, v219, 2, v2
	ds_read_b32 v191, v191 offset:928
	v_lshl_add_u32 v193, v220, 2, v2
	ds_read_b32 v193, v193 offset:928
	v_lshl_add_u32 v194, v221, 2, v2
	ds_read_b32 v194, v194 offset:928
	v_lshl_add_u32 v195, v222, 2, v2
	ds_read_b32 v195, v195 offset:928
	v_lshl_add_u32 v196, v223, 2, v2
	ds_read_b32 v196, v196 offset:928
	s_waitcnt lgkmcnt(0)
	s_and_saveexec_b64 vcc, s[48:49]
	s_cbranch_execz .LBB0_451
	s_nop 2
	v_fmamk_f32 v14, v162, 0x413504f3, v112

; __device__ __forceinline__ void partialSM(f32x16& p0, f32x16& p1, float& m_reg, float& mn, float& alpha, float C, float thrRaw) {
;     ...
;   float mnC = -mn * C;
; #pragma unroll
;   for (int r = 0; r < 16; ++r) p0[r] = fmaf(p0[r], C, mnC);
; #pragma unroll
;   for (int r = 0; r < 16; ++r) p1[r] = fmaf(p1[r], C, mnC);
; #pragma unroll
;   for (int r = 0; r < 16; ++r) p0[r] = __builtin_amdgcn_exp2f(p0[r]);
; }
; __device__ __forceinline__ void finishSM(f32x16& p0, f32x16& p1, float alpha, float& l_reg, bf16x8& pa0, bf16x8& pa1, bf16x8& pa2, bf16x8& pa3) {
; #pragma unroll
;   for (int r = 0; r < 16; ++r) p1[r] = __builtin_amdgcn_exp2f(p1[r]);
;   float ps = 0;
; #pragma unroll
;   for (int r = 0; r < 16; ++r) ps += p0[r];
; #pragma unroll
;   for (int r = 0; r < 16; ++r) ps += p1[r];
;   { auto rr = __builtin_amdgcn_permlane32_swap(__float_as_uint(ps), __float_as_uint(ps), false, false);
;     ps = __uint_as_float(rr[0]) + __uint_as_float(rr[1]); }
;   l_reg = l_reg * alpha + ps;
;     ...
;   PK4(p0, 0, pa0); PK4(p0, 8, pa1); PK4(p1, 0, pa2); PK4(p1, 8, pa3);
;     ...
; }
; template <int DK, bool QL>
; __device__ __forceinline__ void qkt(f32x16& p0, f32x16& p1, const bf16* Ks, const bf16x8* qr, const char* ql, int r32, int hi) {
;   p0 = f32x16{}; p1 = f32x16{};
; #pragma unroll
;   for (int d0 = 0; d0 < DK / 16; ++d0) { int cb = (d0 * 16 + hi * 8) * 2;
;     const bf16x8 qv = QL ? *reinterpret_cast<const bf16x8*>(ql + d0 * 1024) : qr[d0];
;     bf16x8 b0 = *reinterpret_cast<const bf16x8*>((const char*)Ks + kswz<DK>(r32, cb));
;     bf16x8 b1 = *reinterpret_cast<const bf16x8*>((const char*)Ks + kswz<DK>(32 + r32, cb));
;     p0 = __builtin_amdgcn_mfma_f32_32x32x16_bf16(b0, qv, p0, 0, 0, 0);
;     p1 = __builtin_amdgcn_mfma_f32_32x32x16_bf16(b1, qv, p1, 0, 0, 0); }
; }
; __device__ __forceinline__ void na_hook(f32x16& p0, f32x16& p1, int kr, int q_row, int q_col, int win_r, int win_c, const float* rpb, float inv_scale, int hi) {
;   const bool rowok = (kr >= win_r) && (kr < win_r + 8);
;   int ir = kr - q_row + 7; ir = ir < 0 ? 0 : (ir > 14 ? 14 : ir);
;   const float* rp = rpb + ir * 31;
; #pragma unroll
;   for (int r = 0; r < 16; ++r) {
;     const int kc = crow(r, hi);
;     { const bool ok = rowok && kc >= win_c && kc < win_c + 16; int ic = kc - q_col + 15; ic = ic < 0 ? 0 : (ic > 30 ? 30 : ic);
;       p0[r] = ok ? fmaf(rp[ic], inv_scale, p0[r]) : -1e30f; }
.LBB0_517:
	v_cndmask_b32_e64 v116, v2, v237, s[36:37]
	v_mul_f32_e32 v127, 0xbe0293ee, v116
	v_fmamk_f32 v2, v14, 0x3e0293ee, v127
	v_fmamk_f32 v3, v96, 0x3e0293ee, v127
	v_fmamk_f32 v4, v243, 0x3e0293ee, v127
	v_fmamk_f32 v5, v244, 0x3e0293ee, v127
	v_fmamk_f32 v6, v115, 0x3e0293ee, v127
	v_fmamk_f32 v7, v245, 0x3e0293ee, v127
	v_fmamk_f32 v8, v117, 0x3e0293ee, v127
	v_fmamk_f32 v11, v118, 0x3e0293ee, v127
	v_fmamk_f32 v14, v119, 0x3e0293ee, v127
	v_fmamk_f32 v80, v120, 0x3e0293ee, v127
	v_fmamk_f32 v81, v121, 0x3e0293ee, v127
	v_fmamk_f32 v82, v122, 0x3e0293ee, v127
	v_fmamk_f32 v83, v123, 0x3e0293ee, v127
	v_fmamk_f32 v84, v124, 0x3e0293ee, v127
	v_fmamk_f32 v85, v125, 0x3e0293ee, v127
	v_fmamk_f32 v86, v126, 0x3e0293ee, v127
	v_fmamk_f32 v124, v0, 0x3e0293ee, v127
	v_exp_f32_e32 v121, v2
	v_exp_f32_e32 v123, v3
	v_exp_f32_e32 v12, v4
	v_exp_f32_e32 v122, v5
	v_exp_f32_e32 v10, v6
	v_exp_f32_e32 v13, v7
	v_exp_f32_e32 v9, v8
	v_exp_f32_e32 v11, v11
	v_exp_f32_e32 v6, v14
	v_exp_f32_e32 v8, v80
	v_exp_f32_e32 v4, v81
	v_exp_f32_e32 v7, v82
	v_exp_f32_e32 v2, v83
	v_exp_f32_e32 v5, v84
	v_exp_f32_e32 v0, v85
	v_exp_f32_e32 v3, v86
	v_fmamk_f32 v125, v15, 0x3e0293ee, v127
	v_fmamk_f32 v126, v97, 0x3e0293ee, v127
	v_fmamk_f32 v130, v98, 0x3e0293ee, v127
	v_fmamk_f32 v131, v99, 0x3e0293ee, v127
	v_fmamk_f32 v132, v100, 0x3e0293ee, v127
	v_fmamk_f32 v133, v101, 0x3e0293ee, v127
	v_fmamk_f32 v134, v102, 0x3e0293ee, v127
	v_fmamk_f32 v135, v103, 0x3e0293ee, v127
	v_fmamk_f32 v136, v104, 0x3e0293ee, v127
	v_fmamk_f32 v137, v105, 0x3e0293ee, v127
	v_fmamk_f32 v138, v106, 0x3e0293ee, v127
	v_fmamk_f32 v139, v107, 0x3e0293ee, v127
	v_fmamk_f32 v140, v108, 0x3e0293ee, v127
	v_fmamk_f32 v141, v109, 0x3e0293ee, v127
	v_fmac_f32_e32 v127, 0x3e0293ee, v110
	s_mov_b64 s[52:53], s[54:55]
	s_waitcnt lgkmcnt(0)
	s_barrier
	ds_write_b128 v152, v[168:171]
	ds_write_b128 v153, v[194:197]
	ds_read_b128 v[80:83], v147
	ds_read_b128 v[84:87], v158 offset:32768
	ds_read_b128 v[88:91], v158 offset:40960
	ds_read_b128 v[142:145], v147 offset:1024
	ds_read_b128 v[244:247], v159 offset:32768
	ds_read_b128 v[164:167], v159 offset:40960
	s_add_i32 s50, s50, -1
	v_readlane_b32 s36, v255, 32
	s_waitcnt lgkmcnt(4)
	v_mfma_f32_32x32x16_bf16 v[96:111], v[84:87], v[80:83], 0
	s_cmp_lt_u32 s50, s36
	v_readlane_b32 s48, v255, 33
	s_cselect_b64 s[36:37], -1, 0
	s_cmp_ge_u32 s50, s48
	s_cselect_b64 s[48:49], -1, 0
	s_add_i32 s51, s51, -1
	s_or_b64 s[36:37], s[36:37], s[48:49]
	s_waitcnt lgkmcnt(3)
	v_mfma_f32_32x32x16_bf16 v[80:95], v[88:91], v[80:83], 0
	ds_read_b128 v[168:171], v147 offset:2048
	ds_read_b128 v[172:175], v160 offset:32768
	ds_read_b128 v[194:197], v160 offset:40960
	v_med3_i32 v14, s51, -7, 7
	s_movk_i32 s48, 0x7c
	v_mul_lo_u32 v14, v14, s48
	v_readlane_b32 s48, v255, 50
	v_add_u32_e32 v14, 0, v14
	v_readlane_b32 s49, v255, 51
	s_nor_b64 s[50:51], s[48:49], s[36:37]
	s_waitcnt lgkmcnt(4)
	v_mfma_f32_32x32x16_bf16 v[96:111], v[244:247], v[142:145], v[96:111]
	v_mov_b32_e32 v115, 0xf149f2ca
	s_waitcnt lgkmcnt(3)
	v_mfma_f32_32x32x16_bf16 v[80:95], v[164:167], v[142:145], v[80:95]
	ds_read_b128 v[142:145], v147 offset:3072
	ds_read_b128 v[164:167], v161 offset:32768
	ds_read_b128 v[244:247], v161 offset:40960
	s_waitcnt lgkmcnt(4)
	v_mfma_f32_32x32x16_bf16 v[96:111], v[172:175], v[168:171], v[96:111]
	s_waitcnt lgkmcnt(3)
	v_mfma_f32_32x32x16_bf16 v[80:95], v[194:197], v[168:171], v[80:95]
	ds_read_b128 v[168:171], v147 offset:4096
	ds_read_b128 v[172:175], v176 offset:32768
	ds_read_b128 v[194:197], v176 offset:40960
	s_waitcnt lgkmcnt(4)
	v_mfma_f32_32x32x16_bf16 v[96:111], v[164:167], v[142:145], v[96:111]
	s_waitcnt lgkmcnt(3)
	v_mfma_f32_32x32x16_bf16 v[80:95], v[244:247], v[142:145], v[80:95]
	ds_read_b128 v[142:145], v147 offset:5120
	ds_read_b128 v[164:167], v177 offset:32768
	ds_read_b128 v[244:247], v177 offset:40960
	s_waitcnt lgkmcnt(4)
	v_mfma_f32_32x32x16_bf16 v[96:111], v[172:175], v[168:171], v[96:111]
	s_waitcnt lgkmcnt(3)
	v_mfma_f32_32x32x16_bf16 v[80:95], v[194:197], v[168:171], v[80:95]
	ds_read_b128 v[168:171], v147 offset:6144
	ds_read_b128 v[172:175], v207 offset:32768
	ds_read_b128 v[194:197], v207 offset:40960
	s_waitcnt lgkmcnt(4)
	v_mfma_f32_32x32x16_bf16 v[96:111], v[164:167], v[142:145], v[96:111]
	s_waitcnt lgkmcnt(3)
	v_mfma_f32_32x32x16_bf16 v[80:95], v[244:247], v[142:145], v[80:95]
	ds_read_b128 v[142:145], v147 offset:7168
	ds_read_b128 v[164:167], v208 offset:32768
	ds_read_b128 v[244:247], v208 offset:40960
	s_waitcnt lgkmcnt(4)
	v_mfma_f32_32x32x16_bf16 v[96:111], v[172:175], v[168:171], v[96:111]
	s_waitcnt lgkmcnt(3)
	v_mfma_f32_32x32x16_bf16 v[80:95], v[194:197], v[168:171], v[80:95]
	s_waitcnt lgkmcnt(1)
	v_mfma_f32_32x32x16_bf16 v[96:111], v[164:167], v[142:145], v[96:111]
	s_waitcnt lgkmcnt(0)
	v_mfma_f32_32x32x16_bf16 v[80:95], v[244:247], v[142:145], v[80:95]
	v_add_u32_e32 v142, 0x10800, v14
	v_mov_b32_e32 v14, 0xf149f2ca
	v_lshl_add_u32 v162, v242, 2, v142
	ds_read_b32 v162, v162 offset:928
	v_lshl_add_u32 v178, v209, 2, v142
	ds_read_b32 v178, v178 offset:928
	v_lshl_add_u32 v179, v210, 2, v142
	ds_read_b32 v179, v179 offset:928
	v_lshl_add_u32 v180, v211, 2, v142
	ds_read_b32 v180, v180 offset:928
	v_lshl_add_u32 v201, v212, 2, v142
	ds_read_b32 v201, v201 offset:928
	v_lshl_add_u32 v202, v213, 2, v142
	ds_read_b32 v202, v202 offset:928
	v_lshl_add_u32 v168, v214, 2, v142
	ds_read_b32 v168, v168 offset:928
	v_lshl_add_u32 v169, v215, 2, v142
	ds_read_b32 v169, v169 offset:928
	v_lshl_add_u32 v170, v216, 2, v142
	ds_read_b32 v170, v170 offset:928
	v_lshl_add_u32 v171, v217, 2, v142
	ds_read_b32 v171, v171 offset:928
	v_lshl_add_u32 v190, v218, 2, v142
	ds_read_b32 v190, v190 offset:928
	v_lshl_add_u32 v191, v219, 2, v142
	ds_read_b32 v191, v191 offset:928
	v_lshl_add_u32 v193, v220, 2, v142
	ds_read_b32 v193, v193 offset:928
	v_lshl_add_u32 v194, v221, 2, v142
	ds_read_b32 v194, v194 offset:928
	v_lshl_add_u32 v195, v222, 2, v142
	ds_read_b32 v195, v195 offset:928
	v_lshl_add_u32 v196, v223, 2, v142
	ds_read_b32 v196, v196 offset:928
	s_waitcnt lgkmcnt(0)
	s_and_saveexec_b64 s[48:49], s[50:51]
	s_cbranch_execz .LBB0_519
	s_nop 2
	v_fmamk_f32 v115, v162, 0x413504f3, v96
